# phase_prep: each workgroup walks its 8 items cyclically from a start depending on block&3, so memory-bound (mlstm/rwkv prep) and compute-bound (s5 pass A) items overlap across the chip
# baseline (speedup 1.0000x reference)
.LBB0_261:
.LBB0_262:
	s_andn2_b64 vcc, exec, s[6:7]
	s_cbranch_vccnz .LBB0_560
	s_cmp_eq_u32 s53, 2
	s_cbranch_scc0 .LBB0_560
	v_mov_b32_e32 v0, v226
	v_mov_b32_e32 v1, v226
	s_mov_b32 s16, s73
	s_and_b32 s2, s73, 3
	s_lshl_b32 s2, s2, 9
	s_add_i32 s16, s16, s2
	s_movk_i32 s99, 8
	s_cmpk_gt_i32 s16, 0x7ff
	s_cbranch_scc1 .LBB0_560
	v_and_b32_e32 v32, 63, v1
	v_ashrrev_i32_e32 v1, 6, v0
	v_lshl_add_u32 v35, v1, 12, 0
	v_mul_u32_u24_e32 v0, 0x1a00, v32
	v_lshlrev_b32_e32 v3, 6, v32
	v_lshlrev_b32_e32 v2, 1, v32
	v_or_b32_e32 v40, 64, v32
	v_add_u32_e32 v4, 0x660, v32
	s_movk_i32 s2, 0x60
	v_add_u32_e32 v6, 0x6a0, v32
	v_add_u32_e32 v33, 0xffffd000, v1
	v_lshlrev_b32_e32 v34, 4, v32
	v_add_u32_e32 v37, 0xfffff000, v1
	v_or_b32_e32 v36, 0x200, v32
	v_or_b32_e32 v38, 0x400, v32
	v_or_b32_e32 v42, 0x240, v32
	v_or_b32_e32 v44, 0x440, v32
	v_or_b32_e32 v46, 0x80, v32
	v_or_b32_e32 v48, 0x280, v32
	v_or_b32_e32 v50, 0x480, v32
	v_or_b32_e32 v52, 0xc0, v32
	v_or_b32_e32 v54, 0x2c0, v32
	v_or_b32_e32 v56, 0x4c0, v32
	v_or_b32_e32 v58, 0x100, v32
	v_or_b32_e32 v60, 0x300, v32
	v_or_b32_e32 v62, 0x500, v32
	v_or_b32_e32 v64, 0x140, v32
	v_or_b32_e32 v66, 0x340, v32
	v_or_b32_e32 v68, 0x540, v32
	v_or_b32_e32 v70, 0x180, v32
	v_or_b32_e32 v72, 0x380, v32
	v_or_b32_e32 v74, 0x580, v32
	v_or_b32_e32 v76, 0x1c0, v32
	v_or_b32_e32 v78, 0x3c0, v32
	v_or_b32_e32 v80, 0x5c0, v32
	v_or_b32_e32 v82, 0x600, v32
	v_cmp_gt_u32_e64 s[6:7], s2, v40
	v_or_b32_e32 v84, 0x640, v32
	v_or_b32_e32 v86, 0x6c0, v32
	v_or_b32_e32 v88, 0x700, v32
	v_or_b32_e32 v90, 0x740, v32
	v_or_b32_e32 v92, 0x780, v32
	v_lshlrev_b32_e32 v94, 2, v0
	v_add_u32_e32 v39, v35, v3
	v_lshlrev_b32_e32 v96, 2, v2
	v_lshlrev_b32_e32 v98, 2, v4
	v_lshlrev_b32_e32 v100, 2, v6
	s_branch .LBB0_268

.LBB0_267:
	s_mov_b32 s2, s54
	s_add_i32 s16, s2, s16
	s_and_b32 s16, s16, 0x7ff
	s_sub_u32 s99, s99, 1
	s_cmp_eq_u32 s99, 0
	s_cbranch_scc1 .LBB0_560
